# static s_setprio 1 for waves 4-7 in both the P7 and P8 main loops (flips replaced by s_nop), loop heads at +4 mod 64
# baseline (speedup 1.0000x reference)
; __device__ __forceinline__ unsigned pk2(float lo, float hi) { unsigned r; asm volatile("v_cvt_pk_bf16_f32 %0, %1, %2" : "=v"(r) : "v"(lo), "v"(hi)); return r; }
;     __device__ __forceinline__ void operator()(const f32x4 (&acc)[2][2][4][2], const Unit& u, int wr, int wc, int fr, int fq) const {
;         const int row0 = u.pm * BM + wr * 64 + fr, col0 = u.pn * HALF + wc * 32 + 8 * fq;
;         float rs[2][4];
; #pragma unroll
;         for (int ai = 0; ai < 2; ++ai)
; #pragma unroll
;             for (int m = 0; m < 4; ++m) rs[ai][m] = ssq[row0 + ai * HALF + m * 16];
; #pragma unroll
;         for (int ai = 0; ai < 2; ++ai)
; #pragma unroll
;             for (int m = 0; m < 4; ++m) { bf16_t* rowp = O + (size_t)(row0 + ai * HALF + m * 16) * DFF + col0; const float rsv = rsqrtf(rs[ai][m] * (1.f / D) + EPS);
;                 const float rs2 = rsv * rsv, nrs = -1.4426950409f * rsv;
;                 float v[8];
; #pragma unroll
;                 for (int n = 0; n < 2; ++n)
; #pragma unroll
;                     for (int j = 0; j < 4; ++j) {
;                         const float g0 = acc[ai][0][m][n][j], u0 = acc[ai][1][m][n][j];
;                         v[n * 4 + j] = (g0 * u0) * (rs2 * __builtin_amdgcn_rcpf(1.0f + __builtin_amdgcn_exp2f(g0 * nrs))); }
;                 u32x4 w; w.x = pk2(v[0], v[1]); w.y = pk2(v[2], v[3]); w.z = pk2(v[4], v[5]); w.w = pk2(v[6], v[7]);
;                 *(u32x4*)rowp = w; }
.LBB0_1490:
	v_lshl_add_u32 v144, s46, 8, v148
	v_ashrrev_i32_e32 v145, 31, v144
	v_lshl_add_u64 v[140:141], v[144:145], 2, s[12:13]
	flat_load_dword v146, v[140:141]
	flat_load_dword v164, v[140:141] offset:64
	flat_load_dword v162, v[140:141] offset:128
	flat_load_dword v160, v[140:141] offset:192
	flat_load_dword v158, v[140:141] offset:512
	flat_load_dword v156, v[140:141] offset:576
	flat_load_dword v154, v[140:141] offset:640
	flat_load_dword v152, v[140:141] offset:704
	v_mov_b32_e32 v166, v126
	v_lshl_or_b32 v142, s54, 7, v150
	v_ashrrev_i32_e32 v143, 31, v142
	v_mov_b64_e32 v[140:141], s[8:9]
	v_or_b32_e32 v165, 16, v144
	v_or_b32_e32 v163, 32, v144
	v_or_b32_e32 v161, 48, v144
	v_add_u32_e32 v159, 0x80, v144
	v_add_u32_e32 v157, 0x90, v144
	v_add_u32_e32 v155, 0xa0, v144
	v_add_u32_e32 v153, 0xb0, v144
	v_mad_i64_i32 v[144:145], s[2:3], v144, s34, v[140:141]
	s_mov_b64 s[22:23], -1
	s_mov_b64 s[56:57], s[94:95]
	s_waitcnt vmcnt(0) lgkmcnt(0)
	v_fmamk_f32 v146, v146, 0x3a000000, v223
	v_cmp_gt_f32_e32 vcc, s29, v146
	v_mul_f32_e32 v147, 0x4b800000, v146
	s_nop 0
	v_cndmask_b32_e32 v146, v146, v147, vcc
	v_rsq_f32_e32 v146, v146
	s_nop 0
	v_mul_f32_e32 v147, 0x45800000, v146
	v_cndmask_b32_e32 v146, v146, v147, vcc
	v_mul_f32_e32 v168, 0xbfb8aa3b, v146
	v_mul_f32_e32 v147, v146, v146
	v_mul_f32_e32 v146, v126, v168
	v_exp_f32_e32 v146, v146
	s_nop 0
	v_add_f32_e32 v146, 1.0, v146
	v_rcp_f32_e32 v167, v146
	v_mov_b32_e32 v146, v122
	v_mul_f32_e32 v122, v127, v168
	v_exp_f32_e32 v122, v122
	v_pk_mul_f32 v[166:167], v[146:147], v[166:167]
	v_mov_b32_e32 v146, v123
	v_mul_f32_e32 v126, v166, v167
	v_add_f32_e32 v122, 1.0, v122
	v_rcp_f32_e32 v167, v122
	v_mov_b32_e32 v166, v127
	v_pk_mul_f32 v[122:123], v[146:147], v[166:167]
	s_nop 0
	v_mul_f32_e32 v127, v122, v123
	v_mul_f32_e32 v122, v128, v168
	v_exp_f32_e32 v122, v122
	v_mov_b32_e32 v146, v124
	v_add_f32_e32 v122, 1.0, v122
	v_rcp_f32_e32 v123, v122
	v_mov_b32_e32 v122, v128
	v_pk_mul_f32 v[122:123], v[146:147], v[122:123]
	s_nop 0
	v_mul_f32_e32 v124, v122, v123
	v_mul_f32_e32 v122, v129, v168
	v_exp_f32_e32 v122, v122
	v_mov_b32_e32 v146, v125
	v_add_f32_e32 v122, 1.0, v122
	v_rcp_f32_e32 v123, v122
	v_mov_b32_e32 v122, v129
	v_pk_mul_f32 v[122:123], v[146:147], v[122:123]
	s_nop 0
	v_mul_f32_e32 v125, v122, v123
	v_mul_f32_e32 v122, v118, v168
	v_exp_f32_e32 v122, v122
	v_mov_b32_e32 v146, v114
	v_mul_f32_e32 v114, v119, v168
	v_exp_f32_e32 v114, v114
	v_add_f32_e32 v122, 1.0, v122
	v_rcp_f32_e32 v123, v122
	v_mov_b32_e32 v122, v118
	v_add_f32_e32 v114, 1.0, v114
	v_pk_mul_f32 v[122:123], v[146:147], v[122:123]
	s_nop 0
	v_mul_f32_e32 v118, v122, v123
	v_rcp_f32_e32 v123, v114
	v_mov_b32_e32 v146, v115
	v_mov_b32_e32 v122, v119
	v_pk_mul_f32 v[114:115], v[146:147], v[122:123]
	s_nop 0
	v_mul_f32_e32 v119, v114, v115
	v_mul_f32_e32 v114, v120, v168
	v_exp_f32_e32 v114, v114
	v_mov_b32_e32 v146, v116
	v_cvt_pk_bf16_f32 v116, v126, v127
	v_add_f32_e32 v114, 1.0, v114
	v_rcp_f32_e32 v115, v114
	v_mov_b32_e32 v114, v120
	v_pk_mul_f32 v[114:115], v[146:147], v[114:115]
	s_nop 0
	v_mul_f32_e32 v122, v114, v115
	v_mul_f32_e32 v114, v121, v168
	v_exp_f32_e32 v114, v114
	v_mov_b32_e32 v146, v117
	v_cvt_pk_bf16_f32 v117, v124, v125
	v_cvt_pk_bf16_f32 v118, v118, v119
	v_add_f32_e32 v114, 1.0, v114
	v_rcp_f32_e32 v115, v114
	v_mov_b32_e32 v114, v121
	v_pk_mul_f32 v[114:115], v[146:147], v[114:115]
	s_nop 0
	v_mul_f32_e32 v123, v114, v115
	v_lshlrev_b64 v[114:115], 1, v[142:143]
	v_lshl_add_u64 v[120:121], v[144:145], 0, v[114:115]
	v_cvt_pk_bf16_f32 v119, v122, v123
	flat_store_dwordx4 v[120:121], v[116:119]
	v_mov_b32_e32 v120, v110
	s_nop 0
	v_fmamk_f32 v118, v164, 0x3a000000, v223
	v_cmp_gt_f32_e32 vcc, s29, v118
	v_mul_f32_e32 v119, 0x4b800000, v118
	v_mad_i64_i32 v[116:117], s[2:3], v165, s34, v[140:141]
	v_cndmask_b32_e32 v118, v118, v119, vcc
	v_rsq_f32_e32 v118, v118
	s_nop 0
	v_mul_f32_e32 v119, 0x45800000, v118
	v_cndmask_b32_e32 v118, v118, v119, vcc
	v_mul_f32_e32 v122, 0xbfb8aa3b, v118
	v_mul_f32_e32 v119, v118, v118
	v_mul_f32_e32 v118, v110, v122
	v_exp_f32_e32 v118, v118
	s_nop 0
	v_add_f32_e32 v118, 1.0, v118
	v_rcp_f32_e32 v121, v118
	v_mov_b32_e32 v118, v106
	v_mul_f32_e32 v106, v111, v122
	v_exp_f32_e32 v106, v106
	v_pk_mul_f32 v[120:121], v[118:119], v[120:121]
	v_mov_b32_e32 v118, v107
	v_mul_f32_e32 v110, v120, v121
	v_add_f32_e32 v106, 1.0, v106
	v_rcp_f32_e32 v121, v106
	v_mov_b32_e32 v120, v111
	v_pk_mul_f32 v[106:107], v[118:119], v[120:121]
	s_nop 0
	v_mul_f32_e32 v111, v106, v107
	v_mul_f32_e32 v106, v112, v122
	v_exp_f32_e32 v106, v106
	v_mov_b32_e32 v118, v108
	v_add_f32_e32 v106, 1.0, v106
	v_rcp_f32_e32 v107, v106
	v_mov_b32_e32 v106, v112
	v_pk_mul_f32 v[106:107], v[118:119], v[106:107]
	s_nop 0
	v_mul_f32_e32 v108, v106, v107
	v_mul_f32_e32 v106, v113, v122
	v_exp_f32_e32 v106, v106
	v_mov_b32_e32 v118, v109
	v_add_f32_e32 v106, 1.0, v106
	v_rcp_f32_e32 v107, v106
	v_mov_b32_e32 v106, v113
	v_pk_mul_f32 v[106:107], v[118:119], v[106:107]
	s_nop 0
	v_mul_f32_e32 v109, v106, v107
	v_mul_f32_e32 v106, v102, v122
	v_exp_f32_e32 v106, v106
	v_mov_b32_e32 v118, v98
	v_mul_f32_e32 v98, v103, v122
	v_exp_f32_e32 v98, v98
	v_add_f32_e32 v106, 1.0, v106
	v_rcp_f32_e32 v107, v106
	v_mov_b32_e32 v106, v102
	v_add_f32_e32 v98, 1.0, v98
	v_pk_mul_f32 v[106:107], v[118:119], v[106:107]
	s_nop 0
	v_mul_f32_e32 v112, v106, v107
	v_rcp_f32_e32 v107, v98
	v_mov_b32_e32 v118, v99
	v_mov_b32_e32 v106, v103
	v_lshl_add_u64 v[102:103], v[116:117], 0, v[114:115]
	v_pk_mul_f32 v[98:99], v[118:119], v[106:107]
	v_mov_b32_e32 v118, v100
	v_mul_f32_e32 v106, v98, v99
; __device__ __forceinline__ unsigned pk2(float lo, float hi) { unsigned r; asm volatile("v_cvt_pk_bf16_f32 %0, %1, %2" : "=v"(r) : "v"(lo), "v"(hi)); return r; }
;     __device__ __forceinline__ void operator()(const f32x4 (&acc)[2][2][4][2], const Unit& u, int wr, int wc, int fr, int fq) const {
;     ...
;             for (int m = 0; m < 4; ++m) { bf16_t* rowp = O + (size_t)(row0 + ai * HALF + m * 16) * DFF + col0; const float rsv = rsqrtf(rs[ai][m] * (1.f / D) + EPS);
;                 const float rs2 = rsv * rsv, nrs = -1.4426950409f * rsv;
;                 float v[8];
; #pragma unroll
;                 for (int n = 0; n < 2; ++n)
; #pragma unroll
;                     for (int j = 0; j < 4; ++j) {
;                         const float g0 = acc[ai][0][m][n][j], u0 = acc[ai][1][m][n][j];
;                         v[n * 4 + j] = (g0 * u0) * (rs2 * __builtin_amdgcn_rcpf(1.0f + __builtin_amdgcn_exp2f(g0 * nrs))); }
;                 u32x4 w; w.x = pk2(v[0], v[1]); w.y = pk2(v[2], v[3]); w.z = pk2(v[4], v[5]); w.w = pk2(v[6], v[7]);
;                 *(u32x4*)rowp = w; }
	v_mul_f32_e32 v98, v104, v122
	v_exp_f32_e32 v98, v98
	s_nop 0
	v_add_f32_e32 v98, 1.0, v98
	v_rcp_f32_e32 v99, v98
	v_mov_b32_e32 v98, v104
	v_pk_mul_f32 v[98:99], v[118:119], v[98:99]
	s_nop 0
	v_mul_f32_e32 v104, v98, v99
	v_mul_f32_e32 v98, v105, v122
	v_exp_f32_e32 v98, v98
	v_mov_b32_e32 v118, v101
	v_add_f32_e32 v98, 1.0, v98
	v_rcp_f32_e32 v99, v98
	v_mov_b32_e32 v98, v105
	v_pk_mul_f32 v[98:99], v[118:119], v[98:99]
	s_nop 0
	v_mul_f32_e32 v101, v98, v99
	v_cvt_pk_bf16_f32 v98, v110, v111
	v_cvt_pk_bf16_f32 v99, v108, v109
	v_cvt_pk_bf16_f32 v100, v112, v106
	v_cvt_pk_bf16_f32 v101, v104, v101
	flat_store_dwordx4 v[102:103], v[98:101]
	v_mov_b32_e32 v102, v94
	s_nop 0
	v_fmamk_f32 v100, v162, 0x3a000000, v223
	v_cmp_gt_f32_e32 vcc, s29, v100
	v_mul_f32_e32 v101, 0x4b800000, v100
	v_mad_i64_i32 v[98:99], s[2:3], v163, s34, v[140:141]
	v_cndmask_b32_e32 v100, v100, v101, vcc
	v_rsq_f32_e32 v100, v100
	s_nop 0
	v_mul_f32_e32 v101, 0x45800000, v100
	v_cndmask_b32_e32 v100, v100, v101, vcc
	v_mul_f32_e32 v104, 0xbfb8aa3b, v100
	v_mul_f32_e32 v101, v100, v100
	v_mul_f32_e32 v100, v94, v104
	v_exp_f32_e32 v100, v100
	s_nop 0
	v_add_f32_e32 v100, 1.0, v100
	v_rcp_f32_e32 v103, v100
	v_mov_b32_e32 v100, v90
	v_mul_f32_e32 v90, v95, v104
	v_exp_f32_e32 v90, v90
	v_pk_mul_f32 v[102:103], v[100:101], v[102:103]
	v_mov_b32_e32 v100, v91
	v_mul_f32_e32 v94, v102, v103
	v_add_f32_e32 v90, 1.0, v90
	v_rcp_f32_e32 v103, v90
	v_mov_b32_e32 v102, v95
	v_pk_mul_f32 v[90:91], v[100:101], v[102:103]
	s_nop 0
	v_mul_f32_e32 v95, v90, v91
	v_mul_f32_e32 v90, v96, v104
	v_exp_f32_e32 v90, v90
	v_mov_b32_e32 v100, v92
	v_add_f32_e32 v90, 1.0, v90
	v_rcp_f32_e32 v91, v90
	v_mov_b32_e32 v90, v96
	v_pk_mul_f32 v[90:91], v[100:101], v[90:91]
	s_nop 0
	v_mul_f32_e32 v92, v90, v91
	v_mul_f32_e32 v90, v97, v104
	v_exp_f32_e32 v90, v90
	v_mov_b32_e32 v100, v93
	v_add_f32_e32 v90, 1.0, v90
	v_rcp_f32_e32 v91, v90
	v_mov_b32_e32 v90, v97
	v_pk_mul_f32 v[90:91], v[100:101], v[90:91]
	s_nop 0
	v_mul_f32_e32 v93, v90, v91
	v_mul_f32_e32 v90, v86, v104
	v_exp_f32_e32 v90, v90
	v_mov_b32_e32 v100, v82
	v_mul_f32_e32 v82, v87, v104
	v_exp_f32_e32 v82, v82
	v_add_f32_e32 v90, 1.0, v90
	v_rcp_f32_e32 v91, v90
	v_mov_b32_e32 v90, v86
	v_add_f32_e32 v82, 1.0, v82
	v_pk_mul_f32 v[90:91], v[100:101], v[90:91]
	s_nop 0
	v_mul_f32_e32 v96, v90, v91
	v_rcp_f32_e32 v91, v82
	v_mov_b32_e32 v100, v83
	v_mov_b32_e32 v90, v87
	v_lshl_add_u64 v[86:87], v[98:99], 0, v[114:115]
	v_pk_mul_f32 v[82:83], v[100:101], v[90:91]
	v_mov_b32_e32 v100, v84
	v_mul_f32_e32 v90, v82, v83
	v_mul_f32_e32 v82, v88, v104
	v_exp_f32_e32 v82, v82
	s_nop 0
	v_add_f32_e32 v82, 1.0, v82
	v_rcp_f32_e32 v83, v82
	v_mov_b32_e32 v82, v88
	v_pk_mul_f32 v[82:83], v[100:101], v[82:83]
	s_nop 0
	v_mul_f32_e32 v88, v82, v83
	v_mul_f32_e32 v82, v89, v104
	v_exp_f32_e32 v82, v82
	v_mov_b32_e32 v100, v85
	v_add_f32_e32 v82, 1.0, v82
	v_rcp_f32_e32 v83, v82
	v_mov_b32_e32 v82, v89
	v_pk_mul_f32 v[82:83], v[100:101], v[82:83]
	s_nop 0
	v_mul_f32_e32 v85, v82, v83
	v_cvt_pk_bf16_f32 v82, v94, v95
	v_cvt_pk_bf16_f32 v83, v92, v93
	v_cvt_pk_bf16_f32 v84, v96, v90
	v_cvt_pk_bf16_f32 v85, v88, v85
	flat_store_dwordx4 v[86:87], v[82:85]
	v_mov_b32_e32 v86, v78
	s_nop 0
	v_fmamk_f32 v84, v160, 0x3a000000, v223
	v_cmp_gt_f32_e32 vcc, s29, v84
	v_mul_f32_e32 v85, 0x4b800000, v84
	v_mad_i64_i32 v[82:83], s[2:3], v161, s34, v[140:141]
	v_cndmask_b32_e32 v84, v84, v85, vcc
	v_rsq_f32_e32 v84, v84
	s_nop 0
	v_mul_f32_e32 v85, 0x45800000, v84
	v_cndmask_b32_e32 v84, v84, v85, vcc
	v_mul_f32_e32 v88, 0xbfb8aa3b, v84
	v_mul_f32_e32 v85, v84, v84
	v_mul_f32_e32 v84, v78, v88
	v_exp_f32_e32 v84, v84
	s_nop 0
	v_add_f32_e32 v84, 1.0, v84
	v_rcp_f32_e32 v87, v84
	v_mov_b32_e32 v84, v74
	v_mul_f32_e32 v74, v79, v88
	v_exp_f32_e32 v74, v74
	v_pk_mul_f32 v[86:87], v[84:85], v[86:87]
	v_mov_b32_e32 v84, v75
	v_mul_f32_e32 v78, v86, v87
	v_add_f32_e32 v74, 1.0, v74
	v_rcp_f32_e32 v87, v74
	v_mov_b32_e32 v86, v79
	v_pk_mul_f32 v[74:75], v[84:85], v[86:87]
	s_nop 0
	v_mul_f32_e32 v79, v74, v75
	v_mul_f32_e32 v74, v80, v88
	v_exp_f32_e32 v74, v74
	v_mov_b32_e32 v84, v76
	v_add_f32_e32 v74, 1.0, v74
	v_rcp_f32_e32 v75, v74
	v_mov_b32_e32 v74, v80
	v_pk_mul_f32 v[74:75], v[84:85], v[74:75]
	s_nop 0
	v_mul_f32_e32 v76, v74, v75
	v_mul_f32_e32 v74, v81, v88
	v_exp_f32_e32 v74, v74
	v_mov_b32_e32 v84, v77
	v_add_f32_e32 v74, 1.0, v74
	v_rcp_f32_e32 v75, v74
	v_mov_b32_e32 v74, v81
	v_pk_mul_f32 v[74:75], v[84:85], v[74:75]
	s_nop 0
	v_mul_f32_e32 v77, v74, v75
	v_mul_f32_e32 v74, v70, v88
	v_exp_f32_e32 v74, v74
	v_mov_b32_e32 v84, v66
	v_mul_f32_e32 v66, v71, v88
	v_exp_f32_e32 v66, v66
	v_add_f32_e32 v74, 1.0, v74
	v_rcp_f32_e32 v75, v74
	v_mov_b32_e32 v74, v70
	v_add_f32_e32 v66, 1.0, v66
	v_pk_mul_f32 v[74:75], v[84:85], v[74:75]
	s_nop 0
	v_mul_f32_e32 v80, v74, v75
	v_rcp_f32_e32 v75, v66
	v_mov_b32_e32 v84, v67
	v_mov_b32_e32 v74, v71
	v_lshl_add_u64 v[70:71], v[82:83], 0, v[114:115]
	v_pk_mul_f32 v[66:67], v[84:85], v[74:75]
	v_mov_b32_e32 v84, v68
	v_mul_f32_e32 v74, v66, v67
	v_mul_f32_e32 v66, v72, v88
	v_exp_f32_e32 v66, v66
	s_nop 0
	v_add_f32_e32 v66, 1.0, v66
	v_rcp_f32_e32 v67, v66
	v_mov_b32_e32 v66, v72
	v_pk_mul_f32 v[66:67], v[84:85], v[66:67]
	s_nop 0
	v_mul_f32_e32 v72, v66, v67
	v_mul_f32_e32 v66, v73, v88
	v_exp_f32_e32 v66, v66
	v_mov_b32_e32 v84, v69
	v_add_f32_e32 v66, 1.0, v66
	v_rcp_f32_e32 v67, v66
	v_mov_b32_e32 v66, v73
	v_pk_mul_f32 v[66:67], v[84:85], v[66:67]
	s_nop 0
	v_mul_f32_e32 v69, v66, v67
	v_cvt_pk_bf16_f32 v66, v78, v79
	v_cvt_pk_bf16_f32 v67, v76, v77
	v_cvt_pk_bf16_f32 v68, v80, v74
	v_cvt_pk_bf16_f32 v69, v72, v69
; __device__ __forceinline__ unsigned pk2(float lo, float hi) { unsigned r; asm volatile("v_cvt_pk_bf16_f32 %0, %1, %2" : "=v"(r) : "v"(lo), "v"(hi)); return r; }
;     __device__ __forceinline__ void operator()(const f32x4 (&acc)[2][2][4][2], const Unit& u, int wr, int wc, int fr, int fq) const {
;     ...
;             for (int m = 0; m < 4; ++m) { bf16_t* rowp = O + (size_t)(row0 + ai * HALF + m * 16) * DFF + col0; const float rsv = rsqrtf(rs[ai][m] * (1.f / D) + EPS);
;                 const float rs2 = rsv * rsv, nrs = -1.4426950409f * rsv;
;                 float v[8];
; #pragma unroll
;                 for (int n = 0; n < 2; ++n)
; #pragma unroll
;                     for (int j = 0; j < 4; ++j) {
;                         const float g0 = acc[ai][0][m][n][j], u0 = acc[ai][1][m][n][j];
;                         v[n * 4 + j] = (g0 * u0) * (rs2 * __builtin_amdgcn_rcpf(1.0f + __builtin_amdgcn_exp2f(g0 * nrs))); }
;                 u32x4 w; w.x = pk2(v[0], v[1]); w.y = pk2(v[2], v[3]); w.z = pk2(v[4], v[5]); w.w = pk2(v[6], v[7]);
;                 *(u32x4*)rowp = w; }
	flat_store_dwordx4 v[70:71], v[66:69]
	v_mov_b32_e32 v70, v62
	s_nop 0
	v_fmamk_f32 v68, v158, 0x3a000000, v223
	v_cmp_gt_f32_e32 vcc, s29, v68
	v_mul_f32_e32 v69, 0x4b800000, v68
	v_mad_i64_i32 v[66:67], s[2:3], v159, s34, v[140:141]
	v_cndmask_b32_e32 v68, v68, v69, vcc
	v_rsq_f32_e32 v68, v68
	s_nop 0
	v_mul_f32_e32 v69, 0x45800000, v68
	v_cndmask_b32_e32 v68, v68, v69, vcc
	v_mul_f32_e32 v72, 0xbfb8aa3b, v68
	v_mul_f32_e32 v69, v68, v68
	v_mul_f32_e32 v68, v62, v72
	v_exp_f32_e32 v68, v68
	s_nop 0
	v_add_f32_e32 v68, 1.0, v68
	v_rcp_f32_e32 v71, v68
	v_mov_b32_e32 v68, v58
	v_mul_f32_e32 v58, v63, v72
	v_exp_f32_e32 v58, v58
	v_pk_mul_f32 v[70:71], v[68:69], v[70:71]
	v_mov_b32_e32 v68, v59
	v_mul_f32_e32 v62, v70, v71
	v_add_f32_e32 v58, 1.0, v58
	v_rcp_f32_e32 v71, v58
	v_mov_b32_e32 v70, v63
	v_pk_mul_f32 v[58:59], v[68:69], v[70:71]
	s_nop 0
	v_mul_f32_e32 v63, v58, v59
	v_mul_f32_e32 v58, v64, v72
	v_exp_f32_e32 v58, v58
	v_mov_b32_e32 v68, v60
	v_add_f32_e32 v58, 1.0, v58
	v_rcp_f32_e32 v59, v58
	v_mov_b32_e32 v58, v64
	v_pk_mul_f32 v[58:59], v[68:69], v[58:59]
	s_nop 0
	v_mul_f32_e32 v60, v58, v59
	v_mul_f32_e32 v58, v65, v72
	v_exp_f32_e32 v58, v58
	v_mov_b32_e32 v68, v61
	v_add_f32_e32 v58, 1.0, v58
	v_rcp_f32_e32 v59, v58
	v_mov_b32_e32 v58, v65
	v_pk_mul_f32 v[58:59], v[68:69], v[58:59]
	s_nop 0
	v_mul_f32_e32 v61, v58, v59
	v_mul_f32_e32 v58, v54, v72
	v_exp_f32_e32 v58, v58
	v_mov_b32_e32 v68, v50
	v_mul_f32_e32 v50, v55, v72
	v_exp_f32_e32 v50, v50
	v_add_f32_e32 v58, 1.0, v58
	v_rcp_f32_e32 v59, v58
	v_mov_b32_e32 v58, v54
	v_add_f32_e32 v50, 1.0, v50
	v_pk_mul_f32 v[58:59], v[68:69], v[58:59]
	s_nop 0
	v_mul_f32_e32 v64, v58, v59
	v_rcp_f32_e32 v59, v50
	v_mov_b32_e32 v68, v51
	v_mov_b32_e32 v58, v55
	v_lshl_add_u64 v[54:55], v[66:67], 0, v[114:115]
	v_pk_mul_f32 v[50:51], v[68:69], v[58:59]
	v_mov_b32_e32 v68, v52
	v_mul_f32_e32 v58, v50, v51
	v_mul_f32_e32 v50, v56, v72
	v_exp_f32_e32 v50, v50
	s_nop 0
	v_add_f32_e32 v50, 1.0, v50
	v_rcp_f32_e32 v51, v50
	v_mov_b32_e32 v50, v56
	v_pk_mul_f32 v[50:51], v[68:69], v[50:51]
	s_nop 0
	v_mul_f32_e32 v56, v50, v51
	v_mul_f32_e32 v50, v57, v72
	v_exp_f32_e32 v50, v50
	v_mov_b32_e32 v68, v53
	v_add_f32_e32 v50, 1.0, v50
	v_rcp_f32_e32 v51, v50
	v_mov_b32_e32 v50, v57
	v_pk_mul_f32 v[50:51], v[68:69], v[50:51]
	s_nop 0
	v_mul_f32_e32 v53, v50, v51
	v_cvt_pk_bf16_f32 v50, v62, v63
	v_cvt_pk_bf16_f32 v51, v60, v61
	v_cvt_pk_bf16_f32 v52, v64, v58
	v_cvt_pk_bf16_f32 v53, v56, v53
	flat_store_dwordx4 v[54:55], v[50:53]
	v_mov_b32_e32 v54, v46
	s_nop 0
	v_fmamk_f32 v52, v156, 0x3a000000, v223
	v_cmp_gt_f32_e32 vcc, s29, v52
	v_mul_f32_e32 v53, 0x4b800000, v52
	v_mad_i64_i32 v[50:51], s[2:3], v157, s34, v[140:141]
	v_cndmask_b32_e32 v52, v52, v53, vcc
	v_rsq_f32_e32 v52, v52
	s_nop 0
	v_mul_f32_e32 v53, 0x45800000, v52
	v_cndmask_b32_e32 v52, v52, v53, vcc
	v_mul_f32_e32 v56, 0xbfb8aa3b, v52
	v_mul_f32_e32 v53, v52, v52
	v_mul_f32_e32 v52, v46, v56
	v_exp_f32_e32 v52, v52
	s_nop 0
	v_add_f32_e32 v52, 1.0, v52
	v_rcp_f32_e32 v55, v52
	v_mov_b32_e32 v52, v42
	v_mul_f32_e32 v42, v47, v56
	v_exp_f32_e32 v42, v42
	v_pk_mul_f32 v[54:55], v[52:53], v[54:55]
	v_mov_b32_e32 v52, v43
	v_mul_f32_e32 v46, v54, v55
	v_add_f32_e32 v42, 1.0, v42
	v_rcp_f32_e32 v55, v42
	v_mov_b32_e32 v54, v47
	v_pk_mul_f32 v[42:43], v[52:53], v[54:55]
	s_nop 0
	v_mul_f32_e32 v47, v42, v43
	v_mul_f32_e32 v42, v48, v56
	v_exp_f32_e32 v42, v42
	v_mov_b32_e32 v52, v44
	v_add_f32_e32 v42, 1.0, v42
	v_rcp_f32_e32 v43, v42
	v_mov_b32_e32 v42, v48
	v_pk_mul_f32 v[42:43], v[52:53], v[42:43]
	s_nop 0
	v_mul_f32_e32 v44, v42, v43
	v_mul_f32_e32 v42, v49, v56
	v_exp_f32_e32 v42, v42
	v_mov_b32_e32 v52, v45
	v_add_f32_e32 v42, 1.0, v42
	v_rcp_f32_e32 v43, v42
	v_mov_b32_e32 v42, v49
	v_pk_mul_f32 v[42:43], v[52:53], v[42:43]
	s_nop 0
	v_mul_f32_e32 v45, v42, v43
	v_mul_f32_e32 v42, v38, v56
	v_exp_f32_e32 v42, v42
	v_mov_b32_e32 v52, v34
	v_mul_f32_e32 v34, v39, v56
	v_exp_f32_e32 v34, v34
	v_add_f32_e32 v42, 1.0, v42
	v_rcp_f32_e32 v43, v42
	v_mov_b32_e32 v42, v38
	v_add_f32_e32 v34, 1.0, v34
	v_pk_mul_f32 v[42:43], v[52:53], v[42:43]
	s_nop 0
	v_mul_f32_e32 v48, v42, v43
	v_rcp_f32_e32 v43, v34
	v_mov_b32_e32 v52, v35
	v_mov_b32_e32 v42, v39
	v_lshl_add_u64 v[38:39], v[50:51], 0, v[114:115]
	v_pk_mul_f32 v[34:35], v[52:53], v[42:43]
	v_mov_b32_e32 v52, v36
	v_mul_f32_e32 v42, v34, v35
	v_mul_f32_e32 v34, v40, v56
	v_exp_f32_e32 v34, v34
	s_nop 0
	v_add_f32_e32 v34, 1.0, v34
	v_rcp_f32_e32 v35, v34
	v_mov_b32_e32 v34, v40
	v_pk_mul_f32 v[34:35], v[52:53], v[34:35]
	s_nop 0
	v_mul_f32_e32 v40, v34, v35
	v_mul_f32_e32 v34, v41, v56
	v_exp_f32_e32 v34, v34
	v_mov_b32_e32 v52, v37
	v_add_f32_e32 v34, 1.0, v34
	v_rcp_f32_e32 v35, v34
	v_mov_b32_e32 v34, v41
	v_pk_mul_f32 v[34:35], v[52:53], v[34:35]
	s_nop 0
	v_mul_f32_e32 v37, v34, v35
	v_cvt_pk_bf16_f32 v34, v46, v47
	v_cvt_pk_bf16_f32 v35, v44, v45
	v_cvt_pk_bf16_f32 v36, v48, v42
	v_cvt_pk_bf16_f32 v37, v40, v37
	flat_store_dwordx4 v[38:39], v[34:37]
	v_mov_b32_e32 v38, v30
	s_nop 0
	v_fmamk_f32 v36, v154, 0x3a000000, v223
	v_cmp_gt_f32_e32 vcc, s29, v36
	v_mul_f32_e32 v37, 0x4b800000, v36
; __device__ __forceinline__ unsigned pk2(float lo, float hi) { unsigned r; asm volatile("v_cvt_pk_bf16_f32 %0, %1, %2" : "=v"(r) : "v"(lo), "v"(hi)); return r; }
; #define PG8_BAR __builtin_amdgcn_s_barrier()
; template <class Epi, class Sched, bool ALIGN_EPI = false, bool SP2 = false>
; __device__ __forceinline__ void gemm_phase(PG8_LAS unsigned char* lds, const Gemm g, const Sched& S, const Epi& E) {
;     ...
;         cur = nxt; cA = nA; cB = nB; ++ui;
;         if constexpr (ALIGN_EPI) { if (wr == 1) PG8_BAR; }
;     __device__ __forceinline__ void operator()(const f32x4 (&acc)[2][2][4][2], const Unit& u, int wr, int wc, int fr, int fq) const {
;     ...
;             for (int m = 0; m < 4; ++m) { bf16_t* rowp = O + (size_t)(row0 + ai * HALF + m * 16) * DFF + col0; const float rsv = rsqrtf(rs[ai][m] * (1.f / D) + EPS);
;                 const float rs2 = rsv * rsv, nrs = -1.4426950409f * rsv;
;                 float v[8];
; #pragma unroll
;                 for (int n = 0; n < 2; ++n)
; #pragma unroll
;                     for (int j = 0; j < 4; ++j) {
;                         const float g0 = acc[ai][0][m][n][j], u0 = acc[ai][1][m][n][j];
;                         v[n * 4 + j] = (g0 * u0) * (rs2 * __builtin_amdgcn_rcpf(1.0f + __builtin_amdgcn_exp2f(g0 * nrs))); }
;                 u32x4 w; w.x = pk2(v[0], v[1]); w.y = pk2(v[2], v[3]); w.z = pk2(v[4], v[5]); w.w = pk2(v[6], v[7]);
;                 *(u32x4*)rowp = w; }
	v_mad_i64_i32 v[34:35], s[2:3], v155, s34, v[140:141]
	v_cndmask_b32_e32 v36, v36, v37, vcc
	v_rsq_f32_e32 v36, v36
	s_nop 0
	v_mul_f32_e32 v37, 0x45800000, v36
	v_cndmask_b32_e32 v36, v36, v37, vcc
	v_mul_f32_e32 v40, 0xbfb8aa3b, v36
	v_mul_f32_e32 v37, v36, v36
	v_mul_f32_e32 v36, v30, v40
	v_exp_f32_e32 v36, v36
	s_nop 0
	v_add_f32_e32 v36, 1.0, v36
	v_rcp_f32_e32 v39, v36
	v_mov_b32_e32 v36, v26
	v_mul_f32_e32 v26, v31, v40
	v_exp_f32_e32 v26, v26
	v_pk_mul_f32 v[38:39], v[36:37], v[38:39]
	v_mov_b32_e32 v36, v27
	v_mul_f32_e32 v30, v38, v39
	v_add_f32_e32 v26, 1.0, v26
	v_rcp_f32_e32 v39, v26
	v_mov_b32_e32 v38, v31
	v_pk_mul_f32 v[26:27], v[36:37], v[38:39]
	s_nop 0
	v_mul_f32_e32 v31, v26, v27
	v_mul_f32_e32 v26, v32, v40
	v_exp_f32_e32 v26, v26
	v_mov_b32_e32 v36, v28
	v_add_f32_e32 v26, 1.0, v26
	v_rcp_f32_e32 v27, v26
	v_mov_b32_e32 v26, v32
	v_pk_mul_f32 v[26:27], v[36:37], v[26:27]
	s_nop 0
	v_mul_f32_e32 v28, v26, v27
	v_mul_f32_e32 v26, v33, v40
	v_exp_f32_e32 v26, v26
	v_mov_b32_e32 v36, v29
	v_add_f32_e32 v26, 1.0, v26
	v_rcp_f32_e32 v27, v26
	v_mov_b32_e32 v26, v33
	v_pk_mul_f32 v[26:27], v[36:37], v[26:27]
	s_nop 0
	v_mul_f32_e32 v29, v26, v27
	v_mul_f32_e32 v26, v22, v40
	v_exp_f32_e32 v26, v26
	v_mov_b32_e32 v36, v18
	v_mul_f32_e32 v18, v23, v40
	v_exp_f32_e32 v18, v18
	v_add_f32_e32 v26, 1.0, v26
	v_rcp_f32_e32 v27, v26
	v_mov_b32_e32 v26, v22
	v_add_f32_e32 v18, 1.0, v18
	v_pk_mul_f32 v[26:27], v[36:37], v[26:27]
	s_nop 0
	v_mul_f32_e32 v32, v26, v27
	v_rcp_f32_e32 v27, v18
	v_mov_b32_e32 v36, v19
	v_mov_b32_e32 v26, v23
	v_lshl_add_u64 v[22:23], v[34:35], 0, v[114:115]
	v_pk_mul_f32 v[18:19], v[36:37], v[26:27]
	v_mov_b32_e32 v36, v20
	v_mul_f32_e32 v26, v18, v19
	v_mul_f32_e32 v18, v24, v40
	v_exp_f32_e32 v18, v18
	s_nop 0
	v_add_f32_e32 v18, 1.0, v18
	v_rcp_f32_e32 v19, v18
	v_mov_b32_e32 v18, v24
	v_pk_mul_f32 v[18:19], v[36:37], v[18:19]
	s_nop 0
	v_mul_f32_e32 v24, v18, v19
	v_mul_f32_e32 v18, v25, v40
	v_exp_f32_e32 v18, v18
	v_mov_b32_e32 v36, v21
	v_add_f32_e32 v18, 1.0, v18
	v_rcp_f32_e32 v19, v18
	v_mov_b32_e32 v18, v25
	v_pk_mul_f32 v[18:19], v[36:37], v[18:19]
	s_nop 0
	v_mul_f32_e32 v21, v18, v19
	v_cvt_pk_bf16_f32 v18, v30, v31
	v_cvt_pk_bf16_f32 v19, v28, v29
	v_cvt_pk_bf16_f32 v20, v32, v26
	v_cvt_pk_bf16_f32 v21, v24, v21
	flat_store_dwordx4 v[22:23], v[18:21]
	v_mov_b32_e32 v22, v14
	s_nop 0
	v_fmamk_f32 v20, v152, 0x3a000000, v223
	v_cmp_gt_f32_e32 vcc, s29, v20
	v_mul_f32_e32 v21, 0x4b800000, v20
	v_mad_i64_i32 v[18:19], s[2:3], v153, s34, v[140:141]
	v_cndmask_b32_e32 v20, v20, v21, vcc
	v_rsq_f32_e32 v20, v20
	s_nop 0
	v_mul_f32_e32 v21, 0x45800000, v20
	v_cndmask_b32_e32 v20, v20, v21, vcc
	v_mul_f32_e32 v24, 0xbfb8aa3b, v20
	v_mul_f32_e32 v21, v20, v20
	v_mul_f32_e32 v20, v14, v24
	v_exp_f32_e32 v20, v20
	s_andn2_b64 vcc, exec, s[40:41]
	v_add_f32_e32 v20, 1.0, v20
	v_rcp_f32_e32 v23, v20
	v_mov_b32_e32 v20, v10
	v_mul_f32_e32 v10, v15, v24
	v_exp_f32_e32 v10, v10
	v_pk_mul_f32 v[22:23], v[20:21], v[22:23]
	v_mov_b32_e32 v20, v11
	v_mul_f32_e32 v14, v22, v23
	v_add_f32_e32 v10, 1.0, v10
	v_rcp_f32_e32 v23, v10
	v_mov_b32_e32 v22, v15
	v_pk_mul_f32 v[10:11], v[20:21], v[22:23]
	s_nop 0
	v_mul_f32_e32 v15, v10, v11
	v_mul_f32_e32 v10, v16, v24
	v_exp_f32_e32 v10, v10
	v_mov_b32_e32 v20, v12
	v_add_f32_e32 v10, 1.0, v10
	v_rcp_f32_e32 v11, v10
	v_mov_b32_e32 v10, v16
	v_pk_mul_f32 v[10:11], v[20:21], v[10:11]
	s_nop 0
	v_mul_f32_e32 v12, v10, v11
	v_mul_f32_e32 v10, v17, v24
	v_exp_f32_e32 v10, v10
	v_mov_b32_e32 v20, v13
	v_add_f32_e32 v10, 1.0, v10
	v_rcp_f32_e32 v11, v10
	v_mov_b32_e32 v10, v17
	v_pk_mul_f32 v[10:11], v[20:21], v[10:11]
	s_nop 0
	v_mul_f32_e32 v13, v10, v11
	v_mul_f32_e32 v10, v6, v24
	v_exp_f32_e32 v10, v10
	v_mov_b32_e32 v20, v2
	v_mul_f32_e32 v2, v7, v24
	v_exp_f32_e32 v2, v2
	v_add_f32_e32 v10, 1.0, v10
	v_rcp_f32_e32 v11, v10
	v_mov_b32_e32 v10, v6
	v_add_f32_e32 v2, 1.0, v2
	v_pk_mul_f32 v[10:11], v[20:21], v[10:11]
	s_nop 0
	v_mul_f32_e32 v16, v10, v11
	v_rcp_f32_e32 v11, v2
	v_mov_b32_e32 v20, v3
	v_mov_b32_e32 v10, v7
	v_lshl_add_u64 v[6:7], v[18:19], 0, v[114:115]
	v_pk_mul_f32 v[2:3], v[20:21], v[10:11]
	v_mov_b32_e32 v20, v4
	v_mul_f32_e32 v10, v2, v3
	v_mul_f32_e32 v2, v8, v24
	v_exp_f32_e32 v2, v2
	s_nop 0
	v_add_f32_e32 v2, 1.0, v2
	v_rcp_f32_e32 v3, v2
	v_mov_b32_e32 v2, v8
	v_pk_mul_f32 v[2:3], v[20:21], v[2:3]
	s_nop 0
	v_mul_f32_e32 v8, v2, v3
	v_mul_f32_e32 v2, v9, v24
	v_exp_f32_e32 v2, v2
	v_mov_b32_e32 v20, v5
	v_add_f32_e32 v2, 1.0, v2
	v_rcp_f32_e32 v3, v2
	v_mov_b32_e32 v2, v9
	v_pk_mul_f32 v[2:3], v[20:21], v[2:3]
	s_nop 0
	v_mul_f32_e32 v5, v2, v3
	v_cvt_pk_bf16_f32 v2, v14, v15
	v_cvt_pk_bf16_f32 v3, v12, v13
	v_cvt_pk_bf16_f32 v4, v16, v10
	v_cvt_pk_bf16_f32 v5, v8, v5
	flat_store_dwordx4 v[6:7], v[2:5]
	s_cbranch_vccnz .LBB0_1483
	s_andn2_b64 vcc, exec, s[14:15]
	s_cbranch_vccnz .LBB0_1482
	s_barrier
	s_branch .LBB0_1482
	s_nop 0
	s_nop 0
	s_nop 0
	s_nop 0
	s_nop 0
	s_nop 0
	s_nop 0
	s_nop 0
	s_nop 0
	s_nop 0
	s_nop 0
	s_nop 0
	s_nop 0
	s_nop 0
	s_nop 0
	s_nop 0
	s_nop 0
	s_nop 0
	s_nop 0
	s_nop 0
	s_nop 0
	s_nop 0
	s_nop 0
	s_nop 0
	s_nop 0
	s_nop 0
	s_nop 0
	s_nop 0
